# FF1 K-loop first SP1 phase: one LDS-DMA after every four ds_reads
# speedup vs baseline: 1.0028x; 1.0028x over previous
.LBB0_211:
	s_add_i32 s73, s58, 2
	s_add_u32 s74, s56, 0x80
	s_addc_u32 s59, s57, 0
	s_add_i32 s78, 0, 0x10000
	s_cmp_eq_u32 s63, s58
	s_cselect_b32 s59, s51, s59
	s_cselect_b32 s58, s55, s74
	v_add_u32_e32 v0, s78, v146
	s_cselect_b32 s75, s45, s72
	s_cselect_b32 s74, s44, s67
	s_add_i32 s80, 0, 0x14000
	ds_read_b128 v[148:151], v0
	ds_read_b128 v[152:155], v0 offset:1024
	ds_read_b128 v[156:159], v0 offset:2048
	ds_read_b128 v[160:163], v0 offset:3072
	v_add_u32_e32 v0, s80, v146
	v_lshl_add_u64 v[142:143], s[56:57], 0, v[136:137]
	s_mov_b32 m0, s31
	s_nop 0
	global_load_lds_dwordx4 v[142:143], off
	ds_read_b128 v[164:167], v0
	ds_read_b128 v[168:171], v0 offset:1024
	ds_read_b128 v[172:175], v0 offset:2048
	ds_read_b128 v[176:179], v0 offset:3072
	v_lshl_add_u64 v[142:143], s[56:57], 0, v[132:133]
	s_mov_b32 m0, s53
	s_nop 0
	global_load_lds_dwordx4 v[142:143], off
	ds_read_b128 v[180:183], v147
	ds_read_b128 v[184:187], v147 offset:1024
	ds_read_b128 v[200:203], v147 offset:2048
	ds_read_b128 v[204:207], v147 offset:3072
	v_lshl_add_u64 v[142:143], s[56:57], 0, v[138:139]
	s_add_i32 m0, s27, 0xc000
	s_nop 0
	global_load_lds_dwordx4 v[142:143], off
	ds_read_b128 v[208:211], v147 offset:4096
	ds_read_b128 v[212:215], v147 offset:5120
	ds_read_b128 v[216:219], v147 offset:6144
	ds_read_b128 v[220:223], v147 offset:7168
	v_lshl_add_u64 v[142:143], s[56:57], 0, v[140:141]
	s_add_i32 m0, s27, 0xe000
	s_nop 0
	global_load_lds_dwordx4 v[142:143], off
	s_waitcnt vmcnt(8)
	s_waitcnt lgkmcnt(0)
	s_barrier
	s_setprio 1
	s_waitcnt lgkmcnt(0)
	v_mfma_f32_16x16x32_bf16 v[122:125], v[148:151], v[180:183], v[122:125]
	v_mfma_f32_16x16x32_bf16 v[126:129], v[156:159], v[180:183], v[126:129]
	v_mfma_f32_16x16x32_bf16 v[110:113], v[148:151], v[200:203], v[110:113]
	v_mfma_f32_16x16x32_bf16 v[106:109], v[156:159], v[200:203], v[106:109]
	v_mfma_f32_16x16x32_bf16 v[94:97], v[148:151], v[208:211], v[94:97]
	v_mfma_f32_16x16x32_bf16 v[90:93], v[156:159], v[208:211], v[90:93]
	v_mfma_f32_16x16x32_bf16 v[78:81], v[148:151], v[216:219], v[78:81]
	v_mfma_f32_16x16x32_bf16 v[74:77], v[156:159], v[216:219], v[74:77]
	v_mfma_f32_16x16x32_bf16 v[122:125], v[152:155], v[184:187], v[122:125]
	v_mfma_f32_16x16x32_bf16 v[126:129], v[160:163], v[184:187], v[126:129]
	v_mfma_f32_16x16x32_bf16 v[110:113], v[152:155], v[204:207], v[110:113]
	v_mfma_f32_16x16x32_bf16 v[106:109], v[160:163], v[204:207], v[106:109]
	v_mfma_f32_16x16x32_bf16 v[94:97], v[152:155], v[212:215], v[94:97]
	v_mfma_f32_16x16x32_bf16 v[90:93], v[160:163], v[212:215], v[90:93]
	v_mfma_f32_16x16x32_bf16 v[78:81], v[152:155], v[220:223], v[78:81]
	v_mfma_f32_16x16x32_bf16 v[74:77], v[160:163], v[220:223], v[74:77]
	s_setprio 0
	s_setprio 1
	v_mfma_f32_16x16x32_bf16 v[118:121], v[164:167], v[180:183], v[118:121]
	v_mfma_f32_16x16x32_bf16 v[114:117], v[172:175], v[180:183], v[114:117]
	v_mfma_f32_16x16x32_bf16 v[102:105], v[164:167], v[200:203], v[102:105]
	v_mfma_f32_16x16x32_bf16 v[98:101], v[172:175], v[200:203], v[98:101]
	v_mfma_f32_16x16x32_bf16 v[86:89], v[164:167], v[208:211], v[86:89]
	v_mfma_f32_16x16x32_bf16 v[82:85], v[172:175], v[208:211], v[82:85]
	v_mfma_f32_16x16x32_bf16 v[70:73], v[164:167], v[216:219], v[70:73]
	v_mfma_f32_16x16x32_bf16 v[66:69], v[172:175], v[216:219], v[66:69]
	v_mfma_f32_16x16x32_bf16 v[118:121], v[168:171], v[184:187], v[118:121]
	v_mfma_f32_16x16x32_bf16 v[114:117], v[176:179], v[184:187], v[114:117]
	v_mfma_f32_16x16x32_bf16 v[102:105], v[168:171], v[204:207], v[102:105]
	v_mfma_f32_16x16x32_bf16 v[98:101], v[176:179], v[204:207], v[98:101]
	v_mfma_f32_16x16x32_bf16 v[86:89], v[168:171], v[212:215], v[86:89]
	v_mfma_f32_16x16x32_bf16 v[82:85], v[176:179], v[212:215], v[82:85]
	v_mfma_f32_16x16x32_bf16 v[70:73], v[168:171], v[220:223], v[70:73]
	v_mfma_f32_16x16x32_bf16 v[66:69], v[176:179], v[220:223], v[66:69]
	s_setprio 0
	s_barrier
	s_add_i32 s78, s78, s5
	v_lshl_add_u64 v[142:143], s[74:75], 0, v[134:135]
	s_mov_b32 m0, s78
	ds_read_b128 v[180:183], v147 offset:16384
	ds_read_b128 v[184:187], v147 offset:17408
	ds_read_b128 v[200:203], v147 offset:18432
	ds_read_b128 v[204:207], v147 offset:19456
	ds_read_b128 v[208:211], v147 offset:20480
	ds_read_b128 v[212:215], v147 offset:21504
	ds_read_b128 v[216:219], v147 offset:22528
	ds_read_b128 v[220:223], v147 offset:23552
	global_load_lds_dwordx4 v[142:143], off
	s_add_i32 m0, s78, 0x2000
	v_lshl_add_u64 v[188:189], s[74:75], 0, v[130:131]
	s_add_u32 s74, s74, s6
	s_addc_u32 s75, s75, s7
	s_add_i32 s78, s80, s5
	global_load_lds_dwordx4 v[188:189], off
	v_lshl_add_u64 v[224:225], s[74:75], 0, v[134:135]
	s_mov_b32 m0, s78
	v_lshl_add_u64 v[226:227], s[74:75], 0, v[130:131]
	global_load_lds_dwordx4 v[224:225], off
	s_add_i32 m0, s78, 0x2000
	v_lshl_add_u64 v[228:229], s[58:59], 0, v[136:137]
	global_load_lds_dwordx4 v[226:227], off
	v_lshl_add_u64 v[230:231], s[58:59], 0, v[132:133]
	s_waitcnt vmcnt(6)
	s_waitcnt lgkmcnt(0)
	s_barrier
	s_setprio 1
	s_waitcnt lgkmcnt(0)
	v_mfma_f32_16x16x32_bf16 v[62:65], v[148:151], v[180:183], v[62:65]
	v_mfma_f32_16x16x32_bf16 v[58:61], v[156:159], v[180:183], v[58:61]
	v_mfma_f32_16x16x32_bf16 v[46:49], v[148:151], v[200:203], v[46:49]
	v_mfma_f32_16x16x32_bf16 v[42:45], v[156:159], v[200:203], v[42:45]
	v_mfma_f32_16x16x32_bf16 v[30:33], v[148:151], v[208:211], v[30:33]
	v_mfma_f32_16x16x32_bf16 v[26:29], v[156:159], v[208:211], v[26:29]
	v_mfma_f32_16x16x32_bf16 v[14:17], v[148:151], v[216:219], v[14:17]
	v_mfma_f32_16x16x32_bf16 v[10:13], v[156:159], v[216:219], v[10:13]
	v_mfma_f32_16x16x32_bf16 v[62:65], v[152:155], v[184:187], v[62:65]
	v_mfma_f32_16x16x32_bf16 v[58:61], v[160:163], v[184:187], v[58:61]
	v_mfma_f32_16x16x32_bf16 v[46:49], v[152:155], v[204:207], v[46:49]
	v_mfma_f32_16x16x32_bf16 v[42:45], v[160:163], v[204:207], v[42:45]
	v_mfma_f32_16x16x32_bf16 v[30:33], v[152:155], v[212:215], v[30:33]
	v_mfma_f32_16x16x32_bf16 v[26:29], v[160:163], v[212:215], v[26:29]
	v_mfma_f32_16x16x32_bf16 v[14:17], v[152:155], v[220:223], v[14:17]
	v_mfma_f32_16x16x32_bf16 v[10:13], v[160:163], v[220:223], v[10:13]
	s_setprio 0
	s_setprio 1
	v_mfma_f32_16x16x32_bf16 v[54:57], v[164:167], v[180:183], v[54:57]
	v_mfma_f32_16x16x32_bf16 v[50:53], v[172:175], v[180:183], v[50:53]
	v_mfma_f32_16x16x32_bf16 v[38:41], v[164:167], v[200:203], v[38:41]
	v_mfma_f32_16x16x32_bf16 v[34:37], v[172:175], v[200:203], v[34:37]
	v_mfma_f32_16x16x32_bf16 v[22:25], v[164:167], v[208:211], v[22:25]
	v_mfma_f32_16x16x32_bf16 v[18:21], v[172:175], v[208:211], v[18:21]
	v_mfma_f32_16x16x32_bf16 v[6:9], v[164:167], v[216:219], v[6:9]
	v_mfma_f32_16x16x32_bf16 v[2:5], v[172:175], v[216:219], v[2:5]
	v_mfma_f32_16x16x32_bf16 v[54:57], v[168:171], v[184:187], v[54:57]
	v_mfma_f32_16x16x32_bf16 v[50:53], v[176:179], v[184:187], v[50:53]
	v_mfma_f32_16x16x32_bf16 v[38:41], v[168:171], v[204:207], v[38:41]
	v_mfma_f32_16x16x32_bf16 v[34:37], v[176:179], v[204:207], v[34:37]
	v_mfma_f32_16x16x32_bf16 v[22:25], v[168:171], v[212:215], v[22:25]
	v_mfma_f32_16x16x32_bf16 v[18:21], v[176:179], v[212:215], v[18:21]
	v_mfma_f32_16x16x32_bf16 v[6:9], v[168:171], v[220:223], v[6:9]
	v_mfma_f32_16x16x32_bf16 v[2:5], v[176:179], v[220:223], v[2:5]
	s_setprio 0
	s_barrier
	s_add_i32 s74, 0, 0x18000
	v_add_u32_e32 v0, s74, v146
	s_add_i32 s75, 0, 0x1c000
	ds_read_b128 v[148:151], v0
	ds_read_b128 v[152:155], v0 offset:1024
	ds_read_b128 v[156:159], v0 offset:2048
	ds_read_b128 v[160:163], v0 offset:3072
	v_add_u32_e32 v0, s75, v146
	ds_read_b128 v[164:167], v0
	ds_read_b128 v[168:171], v0 offset:1024
	ds_read_b128 v[172:175], v0 offset:2048
	ds_read_b128 v[176:179], v0 offset:3072
	s_add_u32 s58, s58, s2
	s_addc_u32 s59, s59, s3
	s_mov_b32 m0, s27
	v_lshl_add_u64 v[232:233], s[58:59], 0, v[136:137]
	s_nop 0
	global_load_lds_dwordx4 v[228:229], off
	s_mov_b32 m0, s28
	s_nop 0
	global_load_lds_dwordx4 v[230:231], off
	s_mov_b32 m0, s29
	s_nop 0
	global_load_lds_dwordx4 v[232:233], off
	v_lshl_add_u64 v[232:233], s[58:59], 0, v[132:133]
	s_mov_b32 m0, s30
	s_nop 0
	global_load_lds_dwordx4 v[232:233], off
	ds_read_b128 v[180:183], v147 offset:32768
	ds_read_b128 v[184:187], v147 offset:33792
	ds_read_b128 v[200:203], v147 offset:34816
	ds_read_b128 v[204:207], v147 offset:35840
	ds_read_b128 v[208:211], v147 offset:36864
	ds_read_b128 v[212:215], v147 offset:37888
	ds_read_b128 v[216:219], v147 offset:38912
	ds_read_b128 v[220:223], v147 offset:39936
	s_waitcnt vmcnt(8)
	s_waitcnt lgkmcnt(0)
	s_barrier
	s_setprio 1
	s_waitcnt lgkmcnt(0)
	v_mfma_f32_16x16x32_bf16 v[122:125], v[148:151], v[180:183], v[122:125]
	v_mfma_f32_16x16x32_bf16 v[126:129], v[156:159], v[180:183], v[126:129]
	v_mfma_f32_16x16x32_bf16 v[110:113], v[148:151], v[200:203], v[110:113]
	v_mfma_f32_16x16x32_bf16 v[106:109], v[156:159], v[200:203], v[106:109]
	v_mfma_f32_16x16x32_bf16 v[94:97], v[148:151], v[208:211], v[94:97]
	v_mfma_f32_16x16x32_bf16 v[90:93], v[156:159], v[208:211], v[90:93]
	v_mfma_f32_16x16x32_bf16 v[78:81], v[148:151], v[216:219], v[78:81]
	v_mfma_f32_16x16x32_bf16 v[74:77], v[156:159], v[216:219], v[74:77]
	v_mfma_f32_16x16x32_bf16 v[122:125], v[152:155], v[184:187], v[122:125]
	v_mfma_f32_16x16x32_bf16 v[126:129], v[160:163], v[184:187], v[126:129]
	v_mfma_f32_16x16x32_bf16 v[110:113], v[152:155], v[204:207], v[110:113]
	v_mfma_f32_16x16x32_bf16 v[106:109], v[160:163], v[204:207], v[106:109]
	v_mfma_f32_16x16x32_bf16 v[94:97], v[152:155], v[212:215], v[94:97]
	v_mfma_f32_16x16x32_bf16 v[90:93], v[160:163], v[212:215], v[90:93]
	v_mfma_f32_16x16x32_bf16 v[78:81], v[152:155], v[220:223], v[78:81]
	v_mfma_f32_16x16x32_bf16 v[74:77], v[160:163], v[220:223], v[74:77]
	s_setprio 0
	s_setprio 1
	v_mfma_f32_16x16x32_bf16 v[118:121], v[164:167], v[180:183], v[118:121]
	v_mfma_f32_16x16x32_bf16 v[114:117], v[172:175], v[180:183], v[114:117]
	v_mfma_f32_16x16x32_bf16 v[102:105], v[164:167], v[200:203], v[102:105]
	v_mfma_f32_16x16x32_bf16 v[98:101], v[172:175], v[200:203], v[98:101]
	v_mfma_f32_16x16x32_bf16 v[86:89], v[164:167], v[208:211], v[86:89]
	v_mfma_f32_16x16x32_bf16 v[82:85], v[172:175], v[208:211], v[82:85]
	v_mfma_f32_16x16x32_bf16 v[70:73], v[164:167], v[216:219], v[70:73]
	v_mfma_f32_16x16x32_bf16 v[66:69], v[172:175], v[216:219], v[66:69]
	v_mfma_f32_16x16x32_bf16 v[118:121], v[168:171], v[184:187], v[118:121]
	v_mfma_f32_16x16x32_bf16 v[114:117], v[176:179], v[184:187], v[114:117]
	v_mfma_f32_16x16x32_bf16 v[102:105], v[168:171], v[204:207], v[102:105]
	v_mfma_f32_16x16x32_bf16 v[98:101], v[176:179], v[204:207], v[98:101]
	v_mfma_f32_16x16x32_bf16 v[86:89], v[168:171], v[212:215], v[86:89]
	v_mfma_f32_16x16x32_bf16 v[82:85], v[176:179], v[212:215], v[82:85]
	v_mfma_f32_16x16x32_bf16 v[70:73], v[168:171], v[220:223], v[70:73]
	v_mfma_f32_16x16x32_bf16 v[66:69], v[176:179], v[220:223], v[66:69]
	s_setprio 0
	s_barrier
	s_add_i32 s58, s74, s5
	v_lshl_add_u64 v[142:143], v[142:143], 0, s[24:25]
	s_mov_b32 m0, s58
	ds_read_b128 v[180:183], v147 offset:49152
	ds_read_b128 v[184:187], v147 offset:50176
	ds_read_b128 v[200:203], v147 offset:51200
	ds_read_b128 v[204:207], v147 offset:52224
	ds_read_b128 v[208:211], v147 offset:53248
	ds_read_b128 v[212:215], v147 offset:54272
	ds_read_b128 v[216:219], v147 offset:55296
	ds_read_b128 v[220:223], v147 offset:56320
	global_load_lds_dwordx4 v[142:143], off
	v_lshl_add_u64 v[142:143], v[188:189], 0, s[24:25]
	s_add_i32 m0, s58, 0x2000
	s_add_i32 s58, s75, s5
	global_load_lds_dwordx4 v[142:143], off
	v_lshl_add_u64 v[142:143], v[224:225], 0, s[24:25]
	s_mov_b32 m0, s58
	s_nop 0
	global_load_lds_dwordx4 v[142:143], off
	v_lshl_add_u64 v[142:143], v[226:227], 0, s[24:25]
	s_add_i32 m0, s58, 0x2000
	s_nop 0
	global_load_lds_dwordx4 v[142:143], off
	s_waitcnt vmcnt(6)
	s_waitcnt lgkmcnt(0)
	s_barrier
	s_setprio 1
	s_waitcnt lgkmcnt(0)
	v_mfma_f32_16x16x32_bf16 v[62:65], v[148:151], v[180:183], v[62:65]
	v_mfma_f32_16x16x32_bf16 v[58:61], v[156:159], v[180:183], v[58:61]
	v_mfma_f32_16x16x32_bf16 v[46:49], v[148:151], v[200:203], v[46:49]
	v_mfma_f32_16x16x32_bf16 v[42:45], v[156:159], v[200:203], v[42:45]
	v_mfma_f32_16x16x32_bf16 v[30:33], v[148:151], v[208:211], v[30:33]
	v_mfma_f32_16x16x32_bf16 v[26:29], v[156:159], v[208:211], v[26:29]
	v_mfma_f32_16x16x32_bf16 v[14:17], v[148:151], v[216:219], v[14:17]
	v_mfma_f32_16x16x32_bf16 v[10:13], v[156:159], v[216:219], v[10:13]
	v_mfma_f32_16x16x32_bf16 v[62:65], v[152:155], v[184:187], v[62:65]
	v_mfma_f32_16x16x32_bf16 v[58:61], v[160:163], v[184:187], v[58:61]
	v_mfma_f32_16x16x32_bf16 v[46:49], v[152:155], v[204:207], v[46:49]
	v_mfma_f32_16x16x32_bf16 v[42:45], v[160:163], v[204:207], v[42:45]
	v_mfma_f32_16x16x32_bf16 v[30:33], v[152:155], v[212:215], v[30:33]
	v_mfma_f32_16x16x32_bf16 v[26:29], v[160:163], v[212:215], v[26:29]
	v_mfma_f32_16x16x32_bf16 v[14:17], v[152:155], v[220:223], v[14:17]
	v_mfma_f32_16x16x32_bf16 v[10:13], v[160:163], v[220:223], v[10:13]
	s_setprio 0
	s_setprio 1
	v_mfma_f32_16x16x32_bf16 v[54:57], v[164:167], v[180:183], v[54:57]
	v_mfma_f32_16x16x32_bf16 v[50:53], v[172:175], v[180:183], v[50:53]
	v_mfma_f32_16x16x32_bf16 v[38:41], v[164:167], v[200:203], v[38:41]
	v_mfma_f32_16x16x32_bf16 v[34:37], v[172:175], v[200:203], v[34:37]
	v_mfma_f32_16x16x32_bf16 v[22:25], v[164:167], v[208:211], v[22:25]
	v_mfma_f32_16x16x32_bf16 v[18:21], v[172:175], v[208:211], v[18:21]
	v_mfma_f32_16x16x32_bf16 v[6:9], v[164:167], v[216:219], v[6:9]
	v_mfma_f32_16x16x32_bf16 v[2:5], v[172:175], v[216:219], v[2:5]
	v_mfma_f32_16x16x32_bf16 v[54:57], v[168:171], v[184:187], v[54:57]
	v_mfma_f32_16x16x32_bf16 v[50:53], v[176:179], v[184:187], v[50:53]
	v_mfma_f32_16x16x32_bf16 v[38:41], v[168:171], v[204:207], v[38:41]
	v_mfma_f32_16x16x32_bf16 v[34:37], v[176:179], v[204:207], v[34:37]
	v_mfma_f32_16x16x32_bf16 v[22:25], v[168:171], v[212:215], v[22:25]
	v_mfma_f32_16x16x32_bf16 v[18:21], v[176:179], v[212:215], v[18:21]
	v_mfma_f32_16x16x32_bf16 v[6:9], v[168:171], v[220:223], v[6:9]
	v_mfma_f32_16x16x32_bf16 v[2:5], v[176:179], v[220:223], v[2:5]
	s_setprio 0
	s_barrier
	s_add_u32 s56, s56, 0x100
	s_addc_u32 s57, s57, 0
	s_add_u32 s67, s67, 0x100
	s_addc_u32 s72, s72, 0
	s_cmp_ge_i32 s73, s60
	s_mov_b32 s58, s73
	s_cbranch_scc0 .LBB0_211
	v_readlane_b32 s74, v236, 30
	v_readlane_b32 s75, v236, 31
	v_readlane_b32 s73, v236, 32
	s_mov_b32 s78, s76
